# nsa_loop_rotation_and_parity_fastpath
# speedup vs baseline: 1.0071x; 1.0071x over previous
.Lnsa_body:
	s_mov_b64 s[0:1], -1
	s_and_b64 vcc, exec, s[40:41]
	s_cbranch_vccnz .LBB0_598

.LBB0_589:
	s_cmp_lt_u32 s4, s55
	s_cbranch_scc0 .Lnsa_diag
	v_lshrrev_b64 v[40:41], s4, v[60:61]
	v_and_b32_e32 v40, 1, v40
	v_cmp_eq_u32_e64 s[6:7], 1, v40
	s_cmp_eq_u64 s[6:7], 0
	s_cbranch_scc1 .LBB0_593
	s_cmp_lg_u32 s63, 0
	s_cbranch_scc1 .Lnsa_fastq1
	s_branch .Lnsa_fastq

.LBB0_595:
	s_add_u32 s0, s48, -1
	s_addc_u32 s1, s49, -1
	s_and_b64 s[48:49], s[0:1], s[48:49]
	s_andn2_b64 vcc, exec, s[50:51]
	s_cbranch_vccz .Lnsa_exit_bar
	s_mov_b32 s4, s64
	s_cmp_eq_u64 s[48:49], 0
	s_cselect_b64 s[50:51], -1, 0
	s_ff1_i32_b64 s64, s[48:49]
	s_cmp_lg_u64 s[48:49], 0
	s_cselect_b64 s[52:53], -1, 0
	s_cbranch_scc0 .Lnsa_rot_bar
	v_lshl_add_u32 v16, s64, 6, v82
	v_ashrrev_i32_e32 v17, 31, v16
	v_lshlrev_b64 v[16:17], 7, v[16:17]
	s_lshl_b32 s42, s64, 7
	v_lshl_add_u64 v[16:17], v[72:73], 0, v[16:17]
	v_lshl_add_u64 v[20:21], v[88:89], 0, s[42:43]
	global_load_dwordx4 v[16:19], v[16:17], off
	s_nop 0
	global_load_dwordx4 v[20:23], v[20:21], off
.Lnsa_rot_bar:
	s_waitcnt lgkmcnt(0)
	s_barrier
	s_branch .Lnsa_body

.Lnsa_fastq:
	s_cmp_lg_u32 s63, 0
	s_cbranch_scc1 .Lnsa_fastq1
	ds_read_b128 v[176:179], v175
	ds_read_b128 v[180:183], v211
	ds_read_b128 v[184:187], v228
	ds_read_b128 v[188:191], v229
	ds_read_b128 v[192:195], v175 offset:64
	ds_read_b128 v[196:199], v211 offset:64
	ds_read_b128 v[200:203], v228 offset:64
	ds_read_b128 v[204:207], v229 offset:64
	v_cndmask_b32_e64 v168, v102, 0, s[6:7]
	v_mov_b32_e32 v169, v168
	v_mov_b32_e32 v170, v168
	v_mov_b32_e32 v171, v168
	ds_read_b128 v[212:215], v231 offset:38912
	ds_read_b128 v[216:219], v231 offset:41216
	ds_read_b128 v[220:223], v231 offset:43520
	ds_read_b128 v[224:227], v252 offset:38912
	ds_read_b128 v[232:235], v231 offset:38976
	ds_read_b128 v[236:239], v231 offset:41280
	s_waitcnt lgkmcnt(10)
	v_mfma_f32_16x16x32_bf16 v[52:55], v[176:179], v[4:7], v[168:171]
	v_mfma_f32_16x16x32_bf16 v[48:51], v[180:183], v[4:7], v[168:171]
	ds_read_b128 v[240:243], v231 offset:43584
	v_mfma_f32_16x16x32_bf16 v[44:47], v[184:187], v[4:7], v[168:171]
	ds_read_b128 v[244:247], v252 offset:38976
	v_mfma_f32_16x16x32_bf16 v[40:43], v[188:191], v[4:7], v[168:171]
	s_waitcnt lgkmcnt(8)
	v_mfma_f32_16x16x32_bf16 v[52:55], v[192:195], v[0:3], v[52:55]
	v_mfma_f32_16x16x32_bf16 v[48:51], v[196:199], v[0:3], v[48:51]
	v_mfma_f32_16x16x32_bf16 v[44:47], v[200:203], v[0:3], v[44:47]
	v_mfma_f32_16x16x32_bf16 v[40:43], v[204:207], v[0:3], v[40:43]
	s_nop 4
	v_max3_f32 v90, v52, v53, v54
	v_max3_f32 v90, v90, v55, v48
	v_max3_f32 v90, v90, v49, v50
	v_max3_f32 v90, v90, v51, v44
	v_max3_f32 v90, v90, v45, v46
	v_max3_f32 v90, v90, v47, v40
	v_max3_f32 v90, v90, v41, v42
	v_max_f32_e32 v90, v90, v43
	v_mov_b32_e32 v124, v90
	s_nop 1
	v_permlane16_swap_b32_e32 v124, v90
	v_max_f32_e32 v90, v90, v124
	v_mov_b32_e32 v124, v90
	s_nop 1
	v_permlane32_swap_b32_e32 v124, v90
	v_max3_f32 v127, v122, v90, v124
	v_sub_f32_e32 v90, v122, v127
	v_mov_b32_e32 v126, v127
	v_exp_f32_e32 v90, v90
	v_cmp_gt_f32_e32 vcc, v127, v122
	s_cbranch_vccz .Lnsa_fastq_norescale
	v_pk_mul_f32 v[38:39], v[38:39], v[90:91] op_sel_hi:[1,0]
	v_pk_mul_f32 v[36:37], v[36:37], v[90:91] op_sel_hi:[1,0]
	v_pk_mul_f32 v[34:35], v[34:35], v[90:91] op_sel_hi:[1,0]
	v_pk_mul_f32 v[32:33], v[32:33], v[90:91] op_sel_hi:[1,0]
	v_pk_mul_f32 v[30:31], v[30:31], v[90:91] op_sel_hi:[1,0]
	v_pk_mul_f32 v[28:29], v[28:29], v[90:91] op_sel_hi:[1,0]
	v_pk_mul_f32 v[26:27], v[26:27], v[90:91] op_sel_hi:[1,0]
	v_pk_mul_f32 v[24:25], v[24:25], v[90:91] op_sel_hi:[1,0]

.Lnsa_fastq1:
	ds_read_b128 v[176:179], v175 offset:9472
	ds_read_b128 v[180:183], v211 offset:9472
	ds_read_b128 v[184:187], v228 offset:9472
	ds_read_b128 v[188:191], v229 offset:9472
	ds_read_b128 v[192:195], v175 offset:9536
	ds_read_b128 v[196:199], v211 offset:9536
	ds_read_b128 v[200:203], v228 offset:9536
	ds_read_b128 v[204:207], v229 offset:9536
	v_cndmask_b32_e64 v168, v102, 0, s[6:7]
	v_mov_b32_e32 v169, v168
	v_mov_b32_e32 v170, v168
	v_mov_b32_e32 v171, v168
	ds_read_b128 v[212:215], v231 offset:48128
	ds_read_b128 v[216:219], v231 offset:50432
	ds_read_b128 v[220:223], v231 offset:52736
	ds_read_b128 v[224:227], v252 offset:48128
	ds_read_b128 v[232:235], v231 offset:48192
	ds_read_b128 v[236:239], v231 offset:50496
	s_waitcnt lgkmcnt(10)
	v_mfma_f32_16x16x32_bf16 v[52:55], v[176:179], v[4:7], v[168:171]
	v_mfma_f32_16x16x32_bf16 v[48:51], v[180:183], v[4:7], v[168:171]
	ds_read_b128 v[240:243], v231 offset:52800
	v_mfma_f32_16x16x32_bf16 v[44:47], v[184:187], v[4:7], v[168:171]
	ds_read_b128 v[244:247], v252 offset:48192
	v_mfma_f32_16x16x32_bf16 v[40:43], v[188:191], v[4:7], v[168:171]
	s_waitcnt lgkmcnt(8)
	v_mfma_f32_16x16x32_bf16 v[52:55], v[192:195], v[0:3], v[52:55]
	v_mfma_f32_16x16x32_bf16 v[48:51], v[196:199], v[0:3], v[48:51]
	v_mfma_f32_16x16x32_bf16 v[44:47], v[200:203], v[0:3], v[44:47]
	v_mfma_f32_16x16x32_bf16 v[40:43], v[204:207], v[0:3], v[40:43]
	s_nop 4
	v_max3_f32 v90, v52, v53, v54
	v_max3_f32 v90, v90, v55, v48
	v_max3_f32 v90, v90, v49, v50
	v_max3_f32 v90, v90, v51, v44
	v_max3_f32 v90, v90, v45, v46
	v_max3_f32 v90, v90, v47, v40
	v_max3_f32 v90, v90, v41, v42
	v_max_f32_e32 v90, v90, v43
	v_mov_b32_e32 v124, v90
	s_nop 1
	v_permlane16_swap_b32_e32 v124, v90
	v_max_f32_e32 v90, v90, v124
	v_mov_b32_e32 v124, v90
	s_nop 1
	v_permlane32_swap_b32_e32 v124, v90
	v_max3_f32 v127, v122, v90, v124
	v_sub_f32_e32 v90, v122, v127
	v_mov_b32_e32 v126, v127
	v_exp_f32_e32 v90, v90
	v_cmp_gt_f32_e32 vcc, v127, v122
	s_cbranch_vccz .Lnsa_fastq1_norescale
	v_pk_mul_f32 v[38:39], v[38:39], v[90:91] op_sel_hi:[1,0]
	v_pk_mul_f32 v[36:37], v[36:37], v[90:91] op_sel_hi:[1,0]
	v_pk_mul_f32 v[34:35], v[34:35], v[90:91] op_sel_hi:[1,0]
	v_pk_mul_f32 v[32:33], v[32:33], v[90:91] op_sel_hi:[1,0]
	v_pk_mul_f32 v[30:31], v[30:31], v[90:91] op_sel_hi:[1,0]
	v_pk_mul_f32 v[28:29], v[28:29], v[90:91] op_sel_hi:[1,0]
	v_pk_mul_f32 v[26:27], v[26:27], v[90:91] op_sel_hi:[1,0]
	v_pk_mul_f32 v[24:25], v[24:25], v[90:91] op_sel_hi:[1,0]
